# v20 + hgrn Dm/O rolling LDS prefetch + SEAM3 as hand-written split barrier (side WGs arrive, defer acquire to before merge; recurrence WGs poll TOPGEN)
# speedup vs baseline: 1.0287x; 1.0117x over previous
; __device__ __forceinline__ unsigned xb_ld(unsigned* p)              { return __hip_atomic_load(p, __ATOMIC_RELAXED, __HIP_MEMORY_SCOPE_AGENT); }
; __device__ __forceinline__ unsigned xb_add(unsigned* p, unsigned v) { return __hip_atomic_fetch_add(p, v, __ATOMIC_RELAXED, __HIP_MEMORY_SCOPE_AGENT); }
; #define XB_SPIN(cond, bar) do { unsigned _sp = 0; while (cond) { __builtin_amdgcn_s_sleep(1); \
;     if ((++_sp & 255u) == 0u) { if (xb_ld(&(bar)[XB_TMO])) break; if (_sp > XB_SPIN_CAP) { atomicAdd(&(bar)[XB_TMO], 1u); break; } } } } while (0)
; #define SEAM(k) do { if (IN(k) && IN((k) + 1)) xcd_barrier(bar); STAMP((k) + 1); } while (0)
; __device__ __forceinline__ void xcd_barrier(const XcdBarrier& b) {
;     asm volatile("s_waitcnt vmcnt(0)" ::: "memory");
;     __syncthreads();
;     if (threadIdx.x == 0) {
;         unsigned* bar = b.bar;
;         __builtin_amdgcn_s_waitcnt(0);
;         unsigned nloc = b.st[0], nx = b.st[1];
;         if (nloc == 0u) { xcd_barrier_complete(bar, b.x, nloc, nx); b.st[0] = nloc; b.st[1] = nx; }
;         const unsigned old = xb_add(&bar[XB_XSUB(b.x)], 1u);
;         const unsigned gen = old / nloc;
;         if (old + 1u == (gen + 1u) * nloc) {
;             __builtin_amdgcn_fence(__ATOMIC_RELEASE, "agent");
;             asm volatile("s_waitcnt vmcnt(0)" ::: "memory");
;             const unsigned og = xb_add(&bar[XB_TOP], 1u);
;             const unsigned tg = og / nx;
;             if (og + 1u == (tg + 1u) * nx) xb_add(&bar[XB_TOPGEN], 1u);
;             else XB_SPIN(xb_ld(&bar[XB_TOPGEN]) == tg, bar);
;             __builtin_amdgcn_fence(__ATOMIC_ACQUIRE, "agent");
;             xb_add(&bar[XB_XGEN(b.x)], 1u);
;             asm volatile("s_waitcnt vmcnt(0)" ::: "memory");
;         } else {
;             XB_SPIN(xb_ld(&bar[XB_XGEN(b.x)]) == gen, bar);
;             __builtin_amdgcn_fence(__ATOMIC_ACQUIRE, "agent");
;             asm volatile("s_waitcnt vmcnt(0)" ::: "memory");
;         }
;     }
;     __syncthreads();
; }
; __global__ void __launch_bounds__(512, 2) fwd_megakernel(Args a) {
;     ...
;     SEAM(3);
.LBB0_350:
	s_cmp_gt_i32 s83, 4
	s_cselect_b64 s[0:1], -1, 0
	s_and_b64 s[4:5], s[4:5], s[0:1]
	s_andn2_b64 vcc, exec, s[4:5]
	s_cbranch_vccnz .LBB0_404
	s_waitcnt vmcnt(0) lgkmcnt(0)
	s_barrier
	s_mov_b64 s[4:5], exec
	v_readlane_b32 s6, v248, 2
	v_readlane_b32 s7, v248, 3
	s_and_b64 s[6:7], s[4:5], s[6:7]
	s_mov_b64 exec, s[6:7]
	s_cbranch_execz .Ls3_close
	s_add_i32 s6, 0, 0x27e00
	v_mov_b32_e32 v0, s6
	ds_read2_b32 v[2:3], v0 offset1:1
	v_readlane_b32 s10, v248, 0
	v_readlane_b32 s11, v248, 1
	s_lshl_b32 s6, s3, 8
	s_nop 1
	s_add_u32 s6, s10, s6
	s_addc_u32 s7, s11, 0
	v_mov_b32_e32 v4, 1
	v_mov_b32_e32 v5, 0x1000
	global_atomic_add v6, v5, v4, s[6:7] offset:1024 sc0
	s_waitcnt vmcnt(0) lgkmcnt(0)
	v_cvt_f32_u32_e32 v7, v2
	v_sub_u32_e32 v8, 0, v2
	v_rcp_iflag_f32_e32 v7, v7
	s_nop 0
	v_mul_f32_e32 v7, 0x4f7ffffe, v7
	v_cvt_u32_f32_e32 v7, v7
	v_mul_lo_u32 v8, v8, v7
	v_mul_hi_u32 v8, v7, v8
	v_add_u32_e32 v7, v7, v8
	v_mul_hi_u32 v7, v6, v7
	v_mul_lo_u32 v8, v7, v2
	v_sub_u32_e32 v8, v6, v8
	v_add_u32_e32 v9, 1, v7
	v_cmp_ge_u32_e32 vcc, v8, v2
	s_nop 1
	v_cndmask_b32_e32 v7, v7, v9, vcc
	v_sub_u32_e32 v9, v8, v2
	v_cndmask_b32_e32 v8, v8, v9, vcc
	v_add_u32_e32 v9, 1, v7
	v_cmp_ge_u32_e32 vcc, v8, v2
	s_nop 1
	v_cndmask_b32_e32 v7, v7, v9, vcc
	v_add_u32_e32 v9, 1, v7
	v_readfirstlane_b32 s98, v7
	v_mul_lo_u32 v9, v9, v2
	v_add_u32_e32 v10, 1, v6
	v_cmp_eq_u32_e32 vcc, v10, v9
	s_cbranch_vccz .Ls3_notleader
	buffer_wbl2 sc1
	s_waitcnt vmcnt(0)
	v_mov_b32_e32 v5, 0x3000
	global_atomic_add v11, v5, v4, s[10:11] offset:1024 sc0
	v_add_u32_e32 v9, 1, v7
	v_mul_lo_u32 v9, v9, v3
	s_waitcnt vmcnt(0)
	v_add_u32_e32 v10, 1, v11
	v_cmp_eq_u32_e32 vcc, v10, v9
	s_cbranch_vccz .Ls3_nottop
	global_atomic_add v5, v4, s[10:11] offset:1280
.Ls3_nottop:
	v_mov_b32_e32 v5, 0x2000
	global_atomic_add v5, v4, s[6:7] offset:1024
.Ls3_notleader:
	s_cmp_gt_u32 s2, 63
	s_cbranch_scc1 .Ls3_close
	v_mov_b32_e32 v5, 0x3000
	s_mov_b32 s99, 0
.Ls3_spin:
	global_load_dword v12, v5, s[10:11] offset:1280 sc1
	s_waitcnt vmcnt(0)
	v_cmp_ne_u32_e32 vcc, v12, v7
	s_cbranch_vccnz .Ls3_released
	s_add_u32 s99, s99, 1
	s_cmp_gt_u32 s99, 0x40000
	s_cbranch_scc1 .Ls3_released
	s_sleep 1
	s_branch .Ls3_spin
.Ls3_released:
	s_waitcnt vmcnt(0)
	buffer_inv sc1
	s_waitcnt vmcnt(0)
.Ls3_close:
	s_mov_b64 exec, s[4:5]
	s_waitcnt lgkmcnt(0)
	s_barrier

; __global__ void __launch_bounds__(512, 2) fwd_megakernel(Args a) {
;     ...
;                   asm volatile("s_waitcnt vmcnt(0)" ::: "memory"); __syncthreads();
;                   if (tid == 0) __hip_atomic_fetch_add(dcnt + 64 * (8 * x + (r < 8 ? 6 : 7)), (r < 8 ? 2u : 1u), __ATOMIC_RELAXED, __HIP_MEMORY_SCOPE_AGENT); }
;                 merge_phase((u16*)(dout + DO_OG), (const float*)(ws + WS_COS), (const u16*)(dout + DO_AG), bx - 64, 192);
.LBB0_447:
	s_or_b64 exec, exec, s[6:7]
	s_mov_b64 s[6:7], exec
	v_readlane_b32 s8, v248, 2
	v_readlane_b32 s9, v248, 3
	s_and_b64 s[8:9], s[6:7], s[8:9]
	s_mov_b64 exec, s[8:9]
	s_cbranch_execz .Ls3d_skip
	v_readlane_b32 s10, v248, 0
	v_readlane_b32 s11, v248, 1
	v_mov_b32_e32 v0, 0x3000
	s_mov_b32 s99, 0
	s_nop 3
.Ls3d_spin:
	global_load_dword v2, v0, s[10:11] offset:1280 sc1
	s_waitcnt vmcnt(0)
	v_readfirstlane_b32 s8, v2
	s_nop 3
	s_cmp_lg_u32 s8, s98
	s_cbranch_scc1 .Ls3d_rel
	s_add_u32 s99, s99, 1
	s_cmp_gt_u32 s99, 0x40000
	s_cbranch_scc1 .Ls3d_rel
	s_sleep 1
	s_branch .Ls3d_spin

; __device__ __forceinline__ void merge_phase(u16* OG, const float* LSE, const u16* AG, int bid, int nb) {
;     for (int idx = bid * 512 + threadIdx.x; idx < TT * 64; idx += nb * 512) {
;         const int tok = idx >> 6, h = (idx >> 3) & 7, ch = idx & 7; const size_t off = (size_t)tok * 512 + h * 64 + 8 * ch;
;         const float l0 = LSE[(size_t)tok * 8 + h], l1 = LSE[(size_t)TT * 8 + (size_t)tok * 8 + h], l2 = LSE[(size_t)2 * TT * 8 + (size_t)tok * 8 + h];
; __global__ void __launch_bounds__(512, 2) fwd_megakernel(Args a) {
;     ...
;                 merge_phase((u16*)(dout + DO_OG), (const float*)(ws + WS_COS), (const u16*)(dout + DO_AG), bx - 64, 192);
.Ls3d_skip:
	s_mov_b64 exec, s[6:7]
	s_barrier
	s_add_u32 s4, s76, 0x1000000
	s_addc_u32 s5, s77, 0
	s_lshl_b32 s6, s2, 9
	v_add_u32_e32 v1, s6, v188
	v_add_u32_e32 v0, 0xffff8000, v1
	s_mov_b32 s16, 0x100000
	v_cmp_gt_i32_e32 vcc, s16, v0
	s_and_saveexec_b64 s[6:7], vcc
	s_cbranch_execz .LBB0_450
	s_add_u32 s8, s78, 0x1b00000
	s_addc_u32 s9, s79, 0
	s_add_u32 s10, s76, 0x3000000
	s_addc_u32 s11, s77, 0
	s_add_u32 s12, s76, 0x2000000
	s_addc_u32 s13, s77, 0
	v_add_u32_e32 v2, 0xfffe0000, v1
	v_lshlrev_b32_e32 v3, 3, v0
	s_mov_b64 s[14:15], 0
	v_mov_b32_e32 v1, 0
	s_mov_b32 s17, 0x80000
	s_mov_b32 s18, 0xe7fff

.LBB0_525:
	s_min_u32 s54, s91, 28
	s_lshl_b32 s92, s91, 6
	s_lshl_b32 s54, s54, 6
	s_or_b32 s66, s92, 64
	s_add_i32 s58, s54, 0xc0
	s_add_u32 s54, s62, s58
	s_addc_u32 s55, s63, 0
	v_add_u32_e32 v32, v175, v162
	s_add_u32 s58, s60, s58
	ds_write_b128 v32, v[16:19]
	v_add_u32_e32 v16, v175, v163
	s_addc_u32 s59, 0, 0
	ds_write_b128 v16, v[20:23]
	v_lshl_add_u64 v[16:17], v[88:89], 0, s[66:67]
	s_add_u32 s72, s54, s86
	v_lshlrev_b64 v[16:17], 8, v[16:17]
	s_addc_u32 s73, s55, 0
	v_lshl_add_u64 v[16:17], v[90:91], 0, v[16:17]
	s_lshl_b64 s[72:73], s[72:73], 8
	global_load_dwordx2 v[100:101], v[16:17], off
	global_load_dwordx2 v[98:99], v[16:17], off offset:32
	global_load_dwordx2 v[96:97], v[16:17], off offset:64
	global_load_dwordx2 v[94:95], v[16:17], off offset:96
	v_lshl_add_u64 v[16:17], v[70:71], 0, s[72:73]
	s_lshl_b64 s[58:59], s[58:59], 11
	global_load_dword v194, v[16:17], off
	v_lshl_add_u64 v[16:17], v[72:73], 0, s[58:59]
	s_or_b32 s58, s72, 0x100
	s_mov_b32 s59, s73
	v_lshl_add_u64 v[18:19], v[70:71], 0, s[58:59]
	s_or_b32 s58, s72, 0x200
	global_load_dword v200, v[16:17], off
	global_load_dword v186, v[18:19], off
	global_load_dword v198, v[16:17], off offset:2048
	v_lshl_add_u64 v[18:19], v[70:71], 0, s[58:59]
	global_load_dword v181, v[18:19], off
	v_add_co_u32_e32 v18, vcc, s61, v16
	s_or_b32 s58, s72, 0x300
	s_nop 0
	v_addc_co_u32_e32 v19, vcc, 0, v17, vcc
	v_add_co_u32_e32 v20, vcc, s87, v16
	v_lshl_add_u64 v[22:23], v[70:71], 0, s[58:59]
	s_nop 0
	v_addc_co_u32_e32 v21, vcc, 0, v17, vcc
	s_or_b32 s58, s72, 0x400
	global_load_dword v201, v[20:21], off offset:-4096
	global_load_dword v179, v[22:23], off
	global_load_dword v185, v[18:19], off offset:2048
	v_lshl_add_u64 v[18:19], v[70:71], 0, s[58:59]
	s_or_b32 s58, s72, 0x500
	global_load_dword v177, v[18:19], off
	global_load_dword v196, v[20:21], off
	v_lshl_add_u64 v[18:19], v[70:71], 0, s[58:59]
	s_or_b32 s58, s72, 0x600
	v_add_co_u32_e32 v16, vcc, s88, v16
	global_load_dword v173, v[18:19], off
	global_load_dword v187, v[20:21], off offset:2048
	v_lshl_add_u64 v[18:19], v[70:71], 0, s[58:59]
	v_addc_co_u32_e32 v17, vcc, 0, v17, vcc
	s_or_b32 s72, s72, 0x700
	global_load_dword v166, v[18:19], off
	global_load_dword v167, v[16:17], off
	v_lshl_add_u64 v[18:19], v[70:71], 0, s[72:73]
	global_load_dword v164, v[18:19], off
	global_load_dword v165, v[16:17], off offset:2048
	v_mov_b32_e32 v17, s55
	v_or_b32_e32 v16, s54, v93
	v_lshl_add_u64 v[20:21], s[54:55], 0, v[68:69]
	v_lshlrev_b64 v[16:17], 8, v[16:17]
	v_lshlrev_b64 v[20:21], 8, v[20:21]
	v_lshl_add_u64 v[16:17], v[74:75], 0, v[16:17]
	v_lshl_add_u64 v[20:21], v[74:75], 0, v[20:21]
	global_load_dwordx4 v[16:19], v[16:17], off
	s_nop 0
	global_load_dwordx4 v[20:23], v[20:21], off
	ds_read_b128 v[56:59], v218
	ds_read_b128 v[48:51], v218 offset:64
	ds_read_b128 v[44:47], v218 offset:128
	ds_read_b128 v[40:43], v218 offset:192
	ds_read_b128 v[36:39], v204 offset:17408
	ds_read_b128 v[228:231], v204 offset:17472
	ds_read_b128 v[232:235], v204 offset:17536
	ds_read_b128 v[236:239], v204 offset:17600
	s_waitcnt lgkmcnt(3)
	v_mfma_f32_16x16x32_bf16 v[32:35], v[36:39], v[56:59], 0
	s_waitcnt lgkmcnt(2)
	v_mfma_f32_16x16x32_bf16 v[32:35], v[228:231], v[48:51], v[32:35]
	s_waitcnt lgkmcnt(1)
	v_mfma_f32_16x16x32_bf16 v[32:35], v[232:235], v[44:47], v[32:35]
	s_waitcnt lgkmcnt(0)
	v_mfma_f32_16x16x32_bf16 v[32:35], v[236:239], v[40:43], v[32:35]
	ds_read_b128 v[36:39], v204 offset:21760
	ds_read_b128 v[228:231], v204 offset:21824
	ds_read_b128 v[232:235], v204 offset:21888
	ds_read_b128 v[236:239], v204 offset:21952
	s_nop 3
	v_cndmask_b32_e64 v52, 0, v32, s[18:19]
	v_cndmask_b32_e64 v53, 0, v33, s[20:21]
	v_cndmask_b32_e64 v54, 0, v34, s[22:23]
	v_cndmask_b32_e64 v55, 0, v35, s[24:25]
	v_cvt_pk_bf16_f32 v64, v52, v53
	v_cvt_pk_bf16_f32 v65, v54, v55
	s_waitcnt lgkmcnt(3)
	v_mfma_f32_16x16x32_bf16 v[32:35], v[36:39], v[56:59], 0
	s_waitcnt lgkmcnt(2)
	v_mfma_f32_16x16x32_bf16 v[32:35], v[228:231], v[48:51], v[32:35]
	s_waitcnt lgkmcnt(1)
	v_mfma_f32_16x16x32_bf16 v[32:35], v[232:235], v[44:47], v[32:35]
	s_waitcnt lgkmcnt(0)
	v_mfma_f32_16x16x32_bf16 v[32:35], v[236:239], v[40:43], v[32:35]
	ds_read_b128 v[36:39], v204 offset:26112
	ds_read_b128 v[228:231], v204 offset:26176
	ds_read_b128 v[232:235], v204 offset:26240
	ds_read_b128 v[236:239], v204 offset:26304
	s_nop 3
	v_cndmask_b32_e64 v60, 0, v32, s[26:27]
	v_cndmask_b32_e64 v61, 0, v33, s[28:29]
	v_cndmask_b32_e64 v62, 0, v34, s[30:31]
	v_cndmask_b32_e64 v63, 0, v35, s[34:35]
	v_cvt_pk_bf16_f32 v66, v60, v61
	v_cvt_pk_bf16_f32 v67, v62, v63
	s_waitcnt lgkmcnt(3)
	v_mfma_f32_16x16x32_bf16 v[32:35], v[36:39], v[56:59], 0
	s_waitcnt lgkmcnt(2)
	v_mfma_f32_16x16x32_bf16 v[32:35], v[228:231], v[48:51], v[32:35]
	s_waitcnt lgkmcnt(1)
	v_mfma_f32_16x16x32_bf16 v[32:35], v[232:235], v[44:47], v[32:35]
	s_waitcnt lgkmcnt(0)
	v_mfma_f32_16x16x32_bf16 v[32:35], v[236:239], v[40:43], v[32:35]
	ds_read_b128 v[36:39], v204 offset:30464
	ds_read_b128 v[228:231], v204 offset:30528
	ds_read_b128 v[232:235], v204 offset:30592
	ds_read_b128 v[236:239], v204 offset:30656
	s_nop 3
	v_cndmask_b32_e64 v86, 0, v32, s[36:37]
	v_cndmask_b32_e64 v149, 0, v33, s[38:39]
	v_cndmask_b32_e64 v150, 0, v34, s[40:41]
	v_cndmask_b32_e64 v151, 0, v35, s[42:43]
	v_cvt_pk_bf16_f32 v60, v86, v149
	v_cvt_pk_bf16_f32 v61, v150, v151
	v_add_u32_e32 v86, v178, v203
	s_waitcnt lgkmcnt(3)
	v_mfma_f32_16x16x32_bf16 v[32:35], v[36:39], v[56:59], 0
	s_waitcnt lgkmcnt(2)
	v_mfma_f32_16x16x32_bf16 v[32:35], v[228:231], v[48:51], v[32:35]
	s_waitcnt lgkmcnt(1)
	v_mfma_f32_16x16x32_bf16 v[32:35], v[232:235], v[44:47], v[32:35]
	s_waitcnt lgkmcnt(0)
	v_mfma_f32_16x16x32_bf16 v[32:35], v[236:239], v[40:43], v[32:35]
	ds_read_b64_tr_b16 v[150:151], v205 offset:43520
	ds_read_b64_tr_b16 v[152:153], v205 offset:47872
	ds_read_b128 v[228:231], v219
	ds_read_b128 v[232:235], v219 offset:64
	ds_read_b128 v[236:239], v219 offset:128
	ds_read_b128 v[240:243], v219 offset:192
	s_nop 1
	v_cndmask_b32_e64 v32, 0, v32, s[44:45]
	v_cndmask_b32_e64 v33, 0, v33, s[46:47]
	v_cndmask_b32_e64 v34, 0, v34, s[48:49]
	v_cndmask_b32_e64 v35, 0, v35, s[50:51]
	v_cvt_pk_bf16_f32 v62, v32, v33
	v_cvt_pk_bf16_f32 v63, v34, v35
	ds_read_b64_tr_b16 v[32:33], v205 offset:34816
	ds_read_b64_tr_b16 v[34:35], v205 offset:39168
	s_waitcnt lgkmcnt(0)
	v_mfma_f32_16x16x32_bf16 v[32:35], v[32:35], v[64:67], 0
	ds_read_b64_tr_b16 v[36:37], v206 offset:34816
	ds_read_b64_tr_b16 v[38:39], v206 offset:39168
	v_mfma_f32_16x16x32_bf16 v[32:35], v[150:153], v[60:63], v[32:35]
	ds_read_b64_tr_b16 v[150:151], v206 offset:43520
	ds_read_b64_tr_b16 v[152:153], v206 offset:47872
	v_mfma_f32_16x16x32_bf16 v[32:35], v[228:231], v[56:59], v[32:35]
	ds_read_b128 v[228:231], v220
	v_mfma_f32_16x16x32_bf16 v[32:35], v[232:235], v[48:51], v[32:35]
	ds_read_b128 v[232:235], v220 offset:64
	v_mfma_f32_16x16x32_bf16 v[32:35], v[236:239], v[44:47], v[32:35]
	ds_read_b128 v[236:239], v220 offset:128
	v_mfma_f32_16x16x32_bf16 v[32:35], v[240:243], v[40:43], v[32:35]
	ds_read_b128 v[240:243], v220 offset:192
	s_waitcnt lgkmcnt(6)
	v_mfma_f32_16x16x32_bf16 v[36:39], v[36:39], v[64:67], 0
	ds_read_b64_tr_b16 v[52:53], v207 offset:34816
	ds_read_b64_tr_b16 v[54:55], v207 offset:39168
	s_waitcnt lgkmcnt(6)
	v_mfma_f32_16x16x32_bf16 v[36:39], v[150:153], v[60:63], v[36:39]
	ds_read_b64_tr_b16 v[150:151], v207 offset:43520
	ds_read_b64_tr_b16 v[152:153], v207 offset:47872
	s_waitcnt lgkmcnt(7)
	v_mfma_f32_16x16x32_bf16 v[36:39], v[228:231], v[56:59], v[36:39]
	ds_read_b128 v[228:231], v221
	s_waitcnt lgkmcnt(7)
	v_mfma_f32_16x16x32_bf16 v[36:39], v[232:235], v[48:51], v[36:39]
	ds_read_b128 v[232:235], v221 offset:64
	s_waitcnt lgkmcnt(7)
	v_mfma_f32_16x16x32_bf16 v[36:39], v[236:239], v[44:47], v[36:39]
	ds_read_b128 v[236:239], v221 offset:128
	s_waitcnt lgkmcnt(7)
	v_mfma_f32_16x16x32_bf16 v[36:39], v[240:243], v[40:43], v[36:39]
	ds_read_b128 v[240:243], v221 offset:192
	s_waitcnt lgkmcnt(6)
	v_mfma_f32_16x16x32_bf16 v[52:55], v[52:55], v[64:67], 0
	ds_read_b64_tr_b16 v[244:245], v208 offset:34816
	ds_read_b64_tr_b16 v[246:247], v208 offset:39168
	s_waitcnt lgkmcnt(6)
	v_mfma_f32_16x16x32_bf16 v[52:55], v[150:153], v[60:63], v[52:55]
	ds_read_b64_tr_b16 v[150:151], v208 offset:43520
	ds_read_b64_tr_b16 v[152:153], v208 offset:47872
	s_waitcnt lgkmcnt(7)
	v_mfma_f32_16x16x32_bf16 v[52:55], v[228:231], v[56:59], v[52:55]
	ds_read_b128 v[228:231], v222
	s_waitcnt lgkmcnt(7)
	v_mfma_f32_16x16x32_bf16 v[52:55], v[232:235], v[48:51], v[52:55]
	ds_read_b128 v[232:235], v222 offset:64
	s_waitcnt lgkmcnt(7)
	v_mfma_f32_16x16x32_bf16 v[52:55], v[236:239], v[44:47], v[52:55]
	ds_read_b128 v[236:239], v222 offset:128
	s_waitcnt lgkmcnt(7)
	v_mfma_f32_16x16x32_bf16 v[52:55], v[240:243], v[40:43], v[52:55]
	ds_read_b128 v[240:243], v222 offset:192
	s_waitcnt lgkmcnt(6)
	v_mfma_f32_16x16x32_bf16 v[64:67], v[244:247], v[64:67], 0
	s_waitcnt lgkmcnt(4)
	v_mfma_f32_16x16x32_bf16 v[64:67], v[150:153], v[60:63], v[64:67]
	s_waitcnt lgkmcnt(3)
	v_mfma_f32_16x16x32_bf16 v[64:67], v[228:231], v[56:59], v[64:67]
	s_waitcnt lgkmcnt(2)
	v_mfma_f32_16x16x32_bf16 v[64:67], v[232:235], v[48:51], v[64:67]
	s_waitcnt lgkmcnt(1)
	v_mfma_f32_16x16x32_bf16 v[64:67], v[236:239], v[44:47], v[64:67]
	s_waitcnt lgkmcnt(0)
	v_mfma_f32_16x16x32_bf16 v[40:43], v[240:243], v[40:43], v[64:67]
	ds_read_b64_tr_b16 v[60:61], v209 offset:17408
	ds_read_b64_tr_b16 v[62:63], v209 offset:18496
	ds_read_b64_tr_b16 v[48:49], v209 offset:26112
	ds_read_b64_tr_b16 v[50:51], v209 offset:27200
	ds_read_b128 v[44:47], v180
	ds_read_b128 v[56:59], v182
	ds_read_b64_tr_b16 v[244:245], v86 offset:34816
	ds_read_b64_tr_b16 v[246:247], v86 offset:35904
	ds_read_b64_tr_b16 v[228:229], v86 offset:34848
	ds_read_b64_tr_b16 v[230:231], v86 offset:35936
	ds_read_b64_tr_b16 v[150:151], v86 offset:43520
	ds_read_b64_tr_b16 v[152:153], v86 offset:44608
	ds_read_b64_tr_b16 v[240:241], v86 offset:43552
	ds_read_b64_tr_b16 v[242:243], v86 offset:44640
	s_waitcnt lgkmcnt(6)
	v_mfma_f32_16x16x32_bf16 v[64:67], v[60:63], v[244:247], 0
	s_waitcnt lgkmcnt(4)
	v_mfma_f32_16x16x32_bf16 v[236:239], v[60:63], v[228:231], 0
	s_waitcnt lgkmcnt(2)
	v_mfma_f32_16x16x32_bf16 v[64:67], v[48:51], v[150:153], v[64:67]
	s_waitcnt lgkmcnt(0)
	v_mfma_f32_16x16x32_bf16 v[236:239], v[48:51], v[240:243], v[236:239]
	ds_read_b64_tr_b16 v[244:245], v86 offset:34880
	ds_read_b64_tr_b16 v[246:247], v86 offset:35968
	ds_read_b64_tr_b16 v[228:229], v86 offset:34912
	ds_read_b64_tr_b16 v[230:231], v86 offset:36000
	ds_read_b64_tr_b16 v[150:151], v86 offset:43584
	ds_read_b64_tr_b16 v[152:153], v86 offset:44672
	ds_read_b64_tr_b16 v[240:241], v86 offset:43616
	ds_read_b64_tr_b16 v[242:243], v86 offset:44704
	s_nop 3
	v_pk_mul_f32 v[66:67], v[58:59], v[66:67]
	v_pk_mul_f32 v[64:65], v[56:57], v[64:65]
	v_pk_fma_f32 v[104:105], v[104:105], v[46:47], v[66:67]
	v_pk_fma_f32 v[102:103], v[102:103], v[44:45], v[64:65]
	v_pk_mul_f32 v[238:239], v[58:59], v[238:239]
	v_pk_mul_f32 v[236:237], v[56:57], v[236:237]
	v_pk_fma_f32 v[114:115], v[114:115], v[46:47], v[238:239]
	v_pk_fma_f32 v[108:109], v[108:109], v[44:45], v[236:237]
	s_waitcnt lgkmcnt(6)
	v_mfma_f32_16x16x32_bf16 v[64:67], v[60:63], v[244:247], 0
	s_waitcnt lgkmcnt(4)
	v_mfma_f32_16x16x32_bf16 v[236:239], v[60:63], v[228:231], 0
	s_waitcnt lgkmcnt(2)
	v_mfma_f32_16x16x32_bf16 v[64:67], v[48:51], v[150:153], v[64:67]
	s_waitcnt lgkmcnt(0)
	v_mfma_f32_16x16x32_bf16 v[236:239], v[48:51], v[240:243], v[236:239]
	ds_read_b64_tr_b16 v[244:245], v86 offset:34944
	ds_read_b64_tr_b16 v[246:247], v86 offset:36032
	ds_read_b64_tr_b16 v[228:229], v86 offset:34976
	ds_read_b64_tr_b16 v[230:231], v86 offset:36064
	ds_read_b64_tr_b16 v[150:151], v86 offset:43648
	ds_read_b64_tr_b16 v[152:153], v86 offset:44736
	ds_read_b64_tr_b16 v[240:241], v86 offset:43680
	ds_read_b64_tr_b16 v[242:243], v86 offset:44768
	s_nop 3
	v_pk_mul_f32 v[66:67], v[58:59], v[66:67]
	v_pk_mul_f32 v[64:65], v[56:57], v[64:65]
	v_pk_fma_f32 v[112:113], v[112:113], v[46:47], v[66:67]
	v_pk_fma_f32 v[106:107], v[106:107], v[44:45], v[64:65]
	v_pk_mul_f32 v[238:239], v[58:59], v[238:239]
	v_pk_mul_f32 v[236:237], v[56:57], v[236:237]
	v_pk_fma_f32 v[118:119], v[118:119], v[46:47], v[238:239]
	v_pk_fma_f32 v[110:111], v[110:111], v[44:45], v[236:237]
	s_waitcnt lgkmcnt(6)
	v_mfma_f32_16x16x32_bf16 v[64:67], v[60:63], v[244:247], 0
	s_waitcnt lgkmcnt(4)
	v_mfma_f32_16x16x32_bf16 v[236:239], v[60:63], v[228:231], 0
	s_waitcnt lgkmcnt(2)
	v_mfma_f32_16x16x32_bf16 v[64:67], v[48:51], v[150:153], v[64:67]
	s_waitcnt lgkmcnt(0)
	v_mfma_f32_16x16x32_bf16 v[236:239], v[48:51], v[240:243], v[236:239]
	ds_read_b64_tr_b16 v[244:245], v86 offset:35008
	ds_read_b64_tr_b16 v[246:247], v86 offset:36096
	ds_read_b64_tr_b16 v[228:229], v86 offset:35040
	ds_read_b64_tr_b16 v[230:231], v86 offset:36128
	ds_read_b64_tr_b16 v[150:151], v86 offset:43712
	ds_read_b64_tr_b16 v[152:153], v86 offset:44800
	ds_read_b64_tr_b16 v[240:241], v86 offset:43744
	ds_read_b64_tr_b16 v[242:243], v86 offset:44832
	s_nop 3
	v_pk_mul_f32 v[66:67], v[58:59], v[66:67]
	v_pk_mul_f32 v[64:65], v[56:57], v[64:65]
	v_pk_fma_f32 v[122:123], v[122:123], v[46:47], v[66:67]
	v_pk_fma_f32 v[116:117], v[116:117], v[44:45], v[64:65]
	v_pk_mul_f32 v[238:239], v[58:59], v[238:239]
	v_pk_mul_f32 v[236:237], v[56:57], v[236:237]
	v_pk_fma_f32 v[126:127], v[126:127], v[46:47], v[238:239]
	v_pk_fma_f32 v[120:121], v[120:121], v[44:45], v[236:237]
	s_waitcnt lgkmcnt(6)
	v_mfma_f32_16x16x32_bf16 v[64:67], v[60:63], v[244:247], 0
	s_waitcnt lgkmcnt(4)
	v_mfma_f32_16x16x32_bf16 v[60:63], v[60:63], v[228:231], 0
	s_waitcnt lgkmcnt(2)
	v_mfma_f32_16x16x32_bf16 v[64:67], v[48:51], v[150:153], v[64:67]
	s_waitcnt lgkmcnt(0)
	s_barrier
	s_waitcnt lgkmcnt(0)
	v_mfma_f32_16x16x32_bf16 v[48:51], v[48:51], v[240:243], v[60:63]
	s_nop 4
	v_pk_mul_f32 v[66:67], v[58:59], v[66:67]
	v_pk_mul_f32 v[64:65], v[56:57], v[64:65]
	v_pk_fma_f32 v[128:129], v[128:129], v[46:47], v[66:67]
	v_pk_fma_f32 v[124:125], v[124:125], v[44:45], v[64:65]
	s_nop 7
	v_pk_mul_f32 v[48:49], v[56:57], v[48:49]
	v_pk_mul_f32 v[50:51], v[58:59], v[50:51]
	v_pk_fma_f32 v[130:131], v[130:131], v[44:45], v[48:49]
	v_mul_f32_e32 v44, v33, v33
	v_mul_f32_e32 v45, v35, v35
	v_fmac_f32_e32 v44, v32, v32
	v_fmac_f32_e32 v45, v34, v34
	v_pk_fma_f32 v[132:133], v[132:133], v[46:47], v[50:51]
	v_add_f32_e32 v44, v44, v45
	v_mul_f32_e32 v45, v37, v37
	v_mul_f32_e32 v46, v39, v39
	v_fmac_f32_e32 v45, v36, v36
	v_fmac_f32_e32 v46, v38, v38
	v_add_f32_e32 v45, v45, v46
	v_add_f32_e32 v44, v44, v45
	v_mul_f32_e32 v45, v53, v53
	v_mul_f32_e32 v46, v55, v55
	v_fmac_f32_e32 v45, v52, v52
	v_fmac_f32_e32 v46, v54, v54
	v_add_f32_e32 v45, v45, v46
	v_add_f32_e32 v44, v44, v45
	v_mul_f32_e32 v45, v41, v41
	v_mul_f32_e32 v46, v43, v43
	v_fmac_f32_e32 v45, v40, v40
	v_fmac_f32_e32 v46, v42, v42
	v_add_f32_e32 v45, v45, v46
	v_and_b32_e32 v46, 64, v210
	v_add_f32_e32 v44, v44, v45
	v_xor_b32_e32 v45, 16, v210
	v_add_u32_e32 v46, 64, v46
	v_cmp_lt_i32_e32 vcc, v45, v46
	s_nop 1
	v_cndmask_b32_e32 v45, v210, v45, vcc
	v_lshlrev_b32_e32 v249, 2, v45
	ds_bpermute_b32 v45, v249, v44
	s_waitcnt lgkmcnt(0)
	v_add_f32_e32 v44, v44, v45
	v_xor_b32_e32 v45, 32, v210
	v_cmp_lt_i32_e32 vcc, v45, v46
	ds_read_b128 v[46:49], v183
	s_waitcnt lgkmcnt(0)
	v_pk_mul_f32 v[50:51], v[104:105], v[48:49]
	v_pk_mul_f32 v[56:57], v[102:103], v[46:47]
	v_cndmask_b32_e32 v45, v210, v45, vcc
	v_cvt_pk_bf16_f32 v56, v56, v57
	v_cvt_pk_bf16_f32 v57, v50, v51
	ds_write_b64 v223, v[56:57]
	v_pk_mul_f32 v[50:51], v[114:115], v[48:49]
	v_pk_mul_f32 v[56:57], v[108:109], v[46:47]
	v_lshlrev_b32_e32 v250, 2, v45
	v_cvt_pk_bf16_f32 v56, v56, v57
	v_cvt_pk_bf16_f32 v57, v50, v51
	ds_write_b64 v223, v[56:57] offset:4352
	v_pk_mul_f32 v[50:51], v[112:113], v[48:49]
	v_pk_mul_f32 v[56:57], v[106:107], v[46:47]
	ds_bpermute_b32 v45, v250, v44
	v_cvt_pk_bf16_f32 v56, v56, v57
	v_cvt_pk_bf16_f32 v57, v50, v51
	ds_write_b64 v223, v[56:57] offset:8704
	v_pk_mul_f32 v[50:51], v[118:119], v[48:49]
	v_pk_mul_f32 v[56:57], v[110:111], v[46:47]
	s_nop 0
	v_cvt_pk_bf16_f32 v56, v56, v57
	v_cvt_pk_bf16_f32 v57, v50, v51
	ds_write_b64 v223, v[56:57] offset:13056
	v_pk_mul_f32 v[50:51], v[122:123], v[48:49]
	v_pk_mul_f32 v[56:57], v[116:117], v[46:47]
	s_nop 0
	v_cvt_pk_bf16_f32 v56, v56, v57
	v_cvt_pk_bf16_f32 v57, v50, v51
	ds_write_b64 v223, v[56:57] offset:17408
	v_pk_mul_f32 v[50:51], v[126:127], v[48:49]
	v_pk_mul_f32 v[56:57], v[120:121], v[46:47]
	s_nop 0
	v_cvt_pk_bf16_f32 v56, v56, v57
	v_cvt_pk_bf16_f32 v57, v50, v51
	ds_write_b64 v223, v[56:57] offset:21760
	v_pk_mul_f32 v[50:51], v[128:129], v[48:49]
	v_pk_mul_f32 v[56:57], v[124:125], v[46:47]
	v_pk_mul_f32 v[48:49], v[132:133], v[48:49]
	v_pk_mul_f32 v[46:47], v[130:131], v[46:47]
	v_cvt_pk_bf16_f32 v56, v56, v57
	v_cvt_pk_bf16_f32 v57, v50, v51
	v_cvt_pk_bf16_f32 v46, v46, v47
	v_cvt_pk_bf16_f32 v47, v48, v49
	ds_write_b64 v223, v[56:57] offset:26112
	ds_write_b64 v223, v[46:47] offset:30464
	s_and_saveexec_b64 s[72:73], s[16:17]
	s_cbranch_execz .LBB0_527
	s_waitcnt lgkmcnt(6)
	v_add_f32_e32 v44, v44, v45
	ds_write_b32 v184, v44

.LBB0_529:
	s_min_u32 s52, s91, 29
	s_lshl_b32 s52, s52, 6
	s_add_i32 s66, s52, 0x80
	s_min_u32 s52, s91, 27
	s_lshl_b32 s52, s52, 6
	s_add_i32 s54, s52, 0x100
	s_add_u32 s52, s62, s54
	s_addc_u32 s53, s63, 0
	v_add_u32_e32 v32, v161, v162
	s_add_u32 s54, s60, s54
	s_waitcnt vmcnt(27)
	ds_write_b128 v32, v[24:27] offset:34816
	v_add_u32_e32 v24, v161, v163
	s_addc_u32 s55, 0, 0
	s_waitcnt vmcnt(26)
	ds_write_b128 v24, v[28:31] offset:34816
	v_lshl_add_u64 v[24:25], v[88:89], 0, s[66:67]
	s_add_u32 s58, s52, s86
	v_lshlrev_b64 v[24:25], 8, v[24:25]
	s_addc_u32 s59, s53, 0
	v_lshl_add_u64 v[24:25], v[90:91], 0, v[24:25]
	s_lshl_b64 s[58:59], s[58:59], 8
	global_load_dwordx2 v[84:85], v[24:25], off
	global_load_dwordx2 v[82:83], v[24:25], off offset:32
	global_load_dwordx2 v[78:79], v[24:25], off offset:64
	global_load_dwordx2 v[76:77], v[24:25], off offset:96
	v_lshl_add_u64 v[24:25], v[70:71], 0, s[58:59]
	s_lshl_b64 s[54:55], s[54:55], 11
	global_load_dword v145, v[24:25], off
	v_lshl_add_u64 v[24:25], v[72:73], 0, s[54:55]
	s_or_b32 s54, s58, 0x100
	s_mov_b32 s55, s59
	v_lshl_add_u64 v[26:27], v[70:71], 0, s[54:55]
	s_or_b32 s54, s58, 0x200
	global_load_dword v144, v[24:25], off
	global_load_dword v146, v[26:27], off
	global_load_dword v143, v[24:25], off offset:2048
	v_lshl_add_u64 v[26:27], v[70:71], 0, s[54:55]
	global_load_dword v138, v[26:27], off
	v_add_co_u32_e32 v26, vcc, s61, v24
	s_or_b32 s54, s58, 0x300
	s_nop 0
	v_addc_co_u32_e32 v27, vcc, 0, v25, vcc
	v_add_co_u32_e32 v28, vcc, s87, v24
	v_lshl_add_u64 v[30:31], v[70:71], 0, s[54:55]
	s_nop 0
	v_addc_co_u32_e32 v29, vcc, 0, v25, vcc
	s_or_b32 s54, s58, 0x400
	global_load_dword v136, v[28:29], off offset:-4096
	global_load_dword v137, v[30:31], off
	global_load_dword v142, v[26:27], off offset:2048
	v_lshl_add_u64 v[26:27], v[70:71], 0, s[54:55]
	s_or_b32 s54, s58, 0x500
	global_load_dword v135, v[26:27], off
	global_load_dword v134, v[28:29], off
	v_lshl_add_u64 v[26:27], v[70:71], 0, s[54:55]
	s_or_b32 s54, s58, 0x600
	v_add_co_u32_e32 v24, vcc, s88, v24
	global_load_dword v139, v[26:27], off
	global_load_dword v141, v[28:29], off offset:2048
	v_lshl_add_u64 v[26:27], v[70:71], 0, s[54:55]
	v_addc_co_u32_e32 v25, vcc, 0, v25, vcc
	s_or_b32 s58, s58, 0x700
	global_load_dword v148, v[26:27], off
	global_load_dword v147, v[24:25], off
	v_lshl_add_u64 v[26:27], v[70:71], 0, s[58:59]
	global_load_dword v140, v[26:27], off
	global_load_dword v155, v[24:25], off offset:2048
	v_mov_b32_e32 v25, s53
	v_or_b32_e32 v24, s52, v93
	v_lshl_add_u64 v[28:29], s[52:53], 0, v[68:69]
	v_lshlrev_b64 v[24:25], 8, v[24:25]
	v_lshlrev_b64 v[28:29], 8, v[28:29]
	v_lshl_add_u64 v[24:25], v[74:75], 0, v[24:25]
	v_lshl_add_u64 v[28:29], v[74:75], 0, v[28:29]
	global_load_dwordx4 v[24:27], v[24:25], off
	s_nop 0
	global_load_dwordx4 v[28:31], v[28:29], off
	ds_read_b128 v[52:55], v218 offset:52224
	ds_read_b128 v[48:51], v218 offset:52288
	ds_read_b128 v[44:47], v218 offset:52352
	ds_read_b128 v[36:39], v218 offset:52416
	ds_read_b128 v[40:43], v211
	ds_read_b128 v[228:231], v211 offset:64
	ds_read_b128 v[232:235], v211 offset:128
	ds_read_b128 v[236:239], v211 offset:192
	s_waitcnt lgkmcnt(3)
	v_mfma_f32_16x16x32_bf16 v[32:35], v[40:43], v[52:55], 0
	s_waitcnt lgkmcnt(2)
	v_mfma_f32_16x16x32_bf16 v[32:35], v[228:231], v[48:51], v[32:35]
	s_waitcnt lgkmcnt(1)
	v_mfma_f32_16x16x32_bf16 v[32:35], v[232:235], v[44:47], v[32:35]
	s_waitcnt lgkmcnt(0)
	v_mfma_f32_16x16x32_bf16 v[32:35], v[236:239], v[36:39], v[32:35]
	ds_read_b128 v[40:43], v211 offset:4352
	ds_read_b128 v[228:231], v211 offset:4416
	ds_read_b128 v[232:235], v211 offset:4480
	ds_read_b128 v[236:239], v211 offset:4544
	s_nop 3
	v_cndmask_b32_e64 v56, 0, v32, s[18:19]
	v_cndmask_b32_e64 v57, 0, v33, s[20:21]
	v_cndmask_b32_e64 v58, 0, v34, s[22:23]
	v_cndmask_b32_e64 v59, 0, v35, s[24:25]
	v_cvt_pk_bf16_f32 v64, v56, v57
	v_cvt_pk_bf16_f32 v65, v58, v59
	s_waitcnt lgkmcnt(3)
	v_mfma_f32_16x16x32_bf16 v[32:35], v[40:43], v[52:55], 0
	s_waitcnt lgkmcnt(2)
	v_mfma_f32_16x16x32_bf16 v[32:35], v[228:231], v[48:51], v[32:35]
	s_waitcnt lgkmcnt(1)
	v_mfma_f32_16x16x32_bf16 v[32:35], v[232:235], v[44:47], v[32:35]
	s_waitcnt lgkmcnt(0)
	v_mfma_f32_16x16x32_bf16 v[32:35], v[236:239], v[36:39], v[32:35]
	ds_read_b128 v[40:43], v211 offset:8704
	ds_read_b128 v[228:231], v211 offset:8768
	ds_read_b128 v[232:235], v211 offset:8832
	ds_read_b128 v[236:239], v211 offset:8896
	s_nop 3
	v_cndmask_b32_e64 v60, 0, v32, s[26:27]
	v_cndmask_b32_e64 v61, 0, v33, s[28:29]
	v_cndmask_b32_e64 v62, 0, v34, s[30:31]
	v_cndmask_b32_e64 v63, 0, v35, s[34:35]
	v_cvt_pk_bf16_f32 v66, v60, v61
	v_cvt_pk_bf16_f32 v67, v62, v63
	s_waitcnt lgkmcnt(3)
	v_mfma_f32_16x16x32_bf16 v[32:35], v[40:43], v[52:55], 0
	s_waitcnt lgkmcnt(2)
	v_mfma_f32_16x16x32_bf16 v[32:35], v[228:231], v[48:51], v[32:35]
	s_waitcnt lgkmcnt(1)
	v_mfma_f32_16x16x32_bf16 v[32:35], v[232:235], v[44:47], v[32:35]
	s_waitcnt lgkmcnt(0)
	v_mfma_f32_16x16x32_bf16 v[32:35], v[236:239], v[36:39], v[32:35]
	ds_read_b128 v[40:43], v211 offset:13056
	ds_read_b128 v[228:231], v211 offset:13120
	ds_read_b128 v[232:235], v211 offset:13184
	ds_read_b128 v[236:239], v211 offset:13248
	s_nop 3
	v_cndmask_b32_e64 v86, 0, v32, s[36:37]
	v_cndmask_b32_e64 v149, 0, v33, s[38:39]
	v_cndmask_b32_e64 v150, 0, v34, s[40:41]
	v_cndmask_b32_e64 v151, 0, v35, s[42:43]
	v_cvt_pk_bf16_f32 v60, v86, v149
	v_cvt_pk_bf16_f32 v61, v150, v151
	v_add_u32_e32 v86, v192, v203
	s_waitcnt lgkmcnt(3)
	v_mfma_f32_16x16x32_bf16 v[32:35], v[40:43], v[52:55], 0
	s_waitcnt lgkmcnt(2)
	v_mfma_f32_16x16x32_bf16 v[32:35], v[228:231], v[48:51], v[32:35]
	s_waitcnt lgkmcnt(1)
	v_mfma_f32_16x16x32_bf16 v[32:35], v[232:235], v[44:47], v[32:35]
	s_waitcnt lgkmcnt(0)
	v_mfma_f32_16x16x32_bf16 v[32:35], v[236:239], v[36:39], v[32:35]
	ds_read_b64_tr_b16 v[150:151], v212 offset:8704
	ds_read_b64_tr_b16 v[152:153], v212 offset:13056
	ds_read_b128 v[228:231], v219
	ds_read_b128 v[232:235], v219 offset:64
	ds_read_b128 v[236:239], v219 offset:128
	ds_read_b128 v[240:243], v219 offset:192
	s_nop 1
	v_cndmask_b32_e64 v32, 0, v32, s[44:45]
	v_cndmask_b32_e64 v33, 0, v33, s[46:47]
	v_cndmask_b32_e64 v34, 0, v34, s[48:49]
	v_cndmask_b32_e64 v35, 0, v35, s[50:51]
	v_cvt_pk_bf16_f32 v62, v32, v33
	v_cvt_pk_bf16_f32 v63, v34, v35
	ds_read_b64_tr_b16 v[32:33], v212
	ds_read_b64_tr_b16 v[34:35], v212 offset:4352
	s_waitcnt lgkmcnt(0)
	v_mfma_f32_16x16x32_bf16 v[32:35], v[32:35], v[64:67], 0
	ds_read_b64_tr_b16 v[40:41], v214
	ds_read_b64_tr_b16 v[42:43], v214 offset:4352
	v_mfma_f32_16x16x32_bf16 v[32:35], v[150:153], v[60:63], v[32:35]
	ds_read_b64_tr_b16 v[150:151], v214 offset:8704
	ds_read_b64_tr_b16 v[152:153], v214 offset:13056
	v_mfma_f32_16x16x32_bf16 v[32:35], v[228:231], v[52:55], v[32:35]
	ds_read_b128 v[228:231], v220
	v_mfma_f32_16x16x32_bf16 v[32:35], v[232:235], v[48:51], v[32:35]
	ds_read_b128 v[232:235], v220 offset:64
	v_mfma_f32_16x16x32_bf16 v[32:35], v[236:239], v[44:47], v[32:35]
	ds_read_b128 v[236:239], v220 offset:128
	v_mfma_f32_16x16x32_bf16 v[32:35], v[240:243], v[36:39], v[32:35]
	ds_read_b128 v[240:243], v220 offset:192
	s_waitcnt lgkmcnt(6)
	v_mfma_f32_16x16x32_bf16 v[40:43], v[40:43], v[64:67], 0
	ds_read_b64_tr_b16 v[56:57], v215
	ds_read_b64_tr_b16 v[58:59], v215 offset:4352
	s_waitcnt lgkmcnt(6)
	v_mfma_f32_16x16x32_bf16 v[40:43], v[150:153], v[60:63], v[40:43]
	ds_read_b64_tr_b16 v[150:151], v215 offset:8704
	ds_read_b64_tr_b16 v[152:153], v215 offset:13056
	s_waitcnt lgkmcnt(7)
	v_mfma_f32_16x16x32_bf16 v[40:43], v[228:231], v[52:55], v[40:43]
	ds_read_b128 v[228:231], v221
	s_waitcnt lgkmcnt(7)
	v_mfma_f32_16x16x32_bf16 v[40:43], v[232:235], v[48:51], v[40:43]
	ds_read_b128 v[232:235], v221 offset:64
	s_waitcnt lgkmcnt(7)
	v_mfma_f32_16x16x32_bf16 v[40:43], v[236:239], v[44:47], v[40:43]
	ds_read_b128 v[236:239], v221 offset:128
	s_waitcnt lgkmcnt(7)
	v_mfma_f32_16x16x32_bf16 v[40:43], v[240:243], v[36:39], v[40:43]
	ds_read_b128 v[240:243], v221 offset:192
	s_waitcnt lgkmcnt(6)
	v_mfma_f32_16x16x32_bf16 v[56:59], v[56:59], v[64:67], 0
	ds_read_b64_tr_b16 v[244:245], v216
	ds_read_b64_tr_b16 v[246:247], v216 offset:4352
	s_waitcnt lgkmcnt(6)
	v_mfma_f32_16x16x32_bf16 v[56:59], v[150:153], v[60:63], v[56:59]
	ds_read_b64_tr_b16 v[150:151], v216 offset:8704
	ds_read_b64_tr_b16 v[152:153], v216 offset:13056
	s_waitcnt lgkmcnt(7)
	v_mfma_f32_16x16x32_bf16 v[56:59], v[228:231], v[52:55], v[56:59]
	ds_read_b128 v[228:231], v222
	s_waitcnt lgkmcnt(7)
	v_mfma_f32_16x16x32_bf16 v[56:59], v[232:235], v[48:51], v[56:59]
	ds_read_b128 v[232:235], v222 offset:64
	s_waitcnt lgkmcnt(7)
	v_mfma_f32_16x16x32_bf16 v[56:59], v[236:239], v[44:47], v[56:59]
	ds_read_b128 v[236:239], v222 offset:128
	s_waitcnt lgkmcnt(7)
	v_mfma_f32_16x16x32_bf16 v[56:59], v[240:243], v[36:39], v[56:59]
	ds_read_b128 v[240:243], v222 offset:192
	s_waitcnt lgkmcnt(6)
	v_mfma_f32_16x16x32_bf16 v[64:67], v[244:247], v[64:67], 0
	s_waitcnt lgkmcnt(4)
	v_mfma_f32_16x16x32_bf16 v[64:67], v[150:153], v[60:63], v[64:67]
	s_waitcnt lgkmcnt(3)
	v_mfma_f32_16x16x32_bf16 v[64:67], v[228:231], v[52:55], v[64:67]
	s_waitcnt lgkmcnt(2)
	v_mfma_f32_16x16x32_bf16 v[64:67], v[232:235], v[48:51], v[64:67]
	s_waitcnt lgkmcnt(1)
	v_mfma_f32_16x16x32_bf16 v[64:67], v[236:239], v[44:47], v[64:67]
	s_waitcnt lgkmcnt(0)
	v_mfma_f32_16x16x32_bf16 v[36:39], v[240:243], v[36:39], v[64:67]
	ds_read_b64_tr_b16 v[60:61], v217
	ds_read_b64_tr_b16 v[62:63], v217 offset:1088
	ds_read_b64_tr_b16 v[52:53], v217 offset:8704
	ds_read_b64_tr_b16 v[54:55], v217 offset:9792
	ds_read_b128 v[44:47], v193
	ds_read_b128 v[48:51], v195
	ds_read_b64_tr_b16 v[244:245], v86
	ds_read_b64_tr_b16 v[246:247], v86 offset:1088
	ds_read_b64_tr_b16 v[230:231], v86 offset:32
	ds_read_b64_tr_b16 v[232:233], v86 offset:1120
	ds_read_b64_tr_b16 v[150:151], v86 offset:8704
	ds_read_b64_tr_b16 v[152:153], v86 offset:9792
	ds_read_b64_tr_b16 v[240:241], v86 offset:8736
	ds_read_b64_tr_b16 v[242:243], v86 offset:9824
	s_waitcnt lgkmcnt(6)
	v_mfma_f32_16x16x32_bf16 v[64:67], v[60:63], v[244:247], 0
	s_waitcnt lgkmcnt(4)
	v_mfma_f32_16x16x32_bf16 v[236:239], v[60:63], v[230:233], 0
	s_waitcnt lgkmcnt(2)
	v_mfma_f32_16x16x32_bf16 v[64:67], v[52:55], v[150:153], v[64:67]
	s_waitcnt lgkmcnt(0)
	v_mfma_f32_16x16x32_bf16 v[236:239], v[52:55], v[240:243], v[236:239]
	ds_read_b64_tr_b16 v[244:245], v86 offset:64
	ds_read_b64_tr_b16 v[246:247], v86 offset:1152
	ds_read_b64_tr_b16 v[230:231], v86 offset:96
	ds_read_b64_tr_b16 v[232:233], v86 offset:1184
	ds_read_b64_tr_b16 v[150:151], v86 offset:8768
	ds_read_b64_tr_b16 v[152:153], v86 offset:9856
	ds_read_b64_tr_b16 v[240:241], v86 offset:8800
	ds_read_b64_tr_b16 v[242:243], v86 offset:9888
	s_nop 3
	v_pk_mul_f32 v[66:67], v[50:51], v[66:67]
	v_pk_mul_f32 v[64:65], v[48:49], v[64:65]
	v_pk_fma_f32 v[104:105], v[104:105], v[46:47], v[66:67]
	v_pk_fma_f32 v[102:103], v[102:103], v[44:45], v[64:65]
	v_pk_mul_f32 v[238:239], v[50:51], v[238:239]
	v_pk_mul_f32 v[236:237], v[48:49], v[236:237]
	v_pk_fma_f32 v[114:115], v[114:115], v[46:47], v[238:239]
	v_pk_fma_f32 v[108:109], v[108:109], v[44:45], v[236:237]
	s_waitcnt lgkmcnt(6)
	v_mfma_f32_16x16x32_bf16 v[64:67], v[60:63], v[244:247], 0
	s_waitcnt lgkmcnt(4)
	v_mfma_f32_16x16x32_bf16 v[236:239], v[60:63], v[230:233], 0
	s_waitcnt lgkmcnt(2)
	v_mfma_f32_16x16x32_bf16 v[64:67], v[52:55], v[150:153], v[64:67]
	s_waitcnt lgkmcnt(0)
	v_mfma_f32_16x16x32_bf16 v[236:239], v[52:55], v[240:243], v[236:239]
	ds_read_b64_tr_b16 v[244:245], v86 offset:128
	ds_read_b64_tr_b16 v[246:247], v86 offset:1216
	ds_read_b64_tr_b16 v[230:231], v86 offset:160
	ds_read_b64_tr_b16 v[232:233], v86 offset:1248
	ds_read_b64_tr_b16 v[150:151], v86 offset:8832
	ds_read_b64_tr_b16 v[152:153], v86 offset:9920
	ds_read_b64_tr_b16 v[240:241], v86 offset:8864
	ds_read_b64_tr_b16 v[242:243], v86 offset:9952
	s_nop 3
	v_pk_mul_f32 v[66:67], v[50:51], v[66:67]
	v_pk_mul_f32 v[64:65], v[48:49], v[64:65]
	v_pk_fma_f32 v[112:113], v[112:113], v[46:47], v[66:67]
	v_pk_fma_f32 v[106:107], v[106:107], v[44:45], v[64:65]
	v_pk_mul_f32 v[238:239], v[50:51], v[238:239]
	v_pk_mul_f32 v[236:237], v[48:49], v[236:237]
	v_pk_fma_f32 v[118:119], v[118:119], v[46:47], v[238:239]
	v_pk_fma_f32 v[110:111], v[110:111], v[44:45], v[236:237]
	s_waitcnt lgkmcnt(6)
	v_mfma_f32_16x16x32_bf16 v[64:67], v[60:63], v[244:247], 0
	s_waitcnt lgkmcnt(4)
	v_mfma_f32_16x16x32_bf16 v[236:239], v[60:63], v[230:233], 0
	s_waitcnt lgkmcnt(2)
	v_mfma_f32_16x16x32_bf16 v[64:67], v[52:55], v[150:153], v[64:67]
	s_waitcnt lgkmcnt(0)
	v_mfma_f32_16x16x32_bf16 v[236:239], v[52:55], v[240:243], v[236:239]
	ds_read_b64_tr_b16 v[244:245], v86 offset:192
	ds_read_b64_tr_b16 v[246:247], v86 offset:1280
	ds_read_b64_tr_b16 v[230:231], v86 offset:224
	ds_read_b64_tr_b16 v[232:233], v86 offset:1312
	ds_read_b64_tr_b16 v[150:151], v86 offset:8896
	ds_read_b64_tr_b16 v[152:153], v86 offset:9984
	ds_read_b64_tr_b16 v[240:241], v86 offset:8928
	ds_read_b64_tr_b16 v[242:243], v86 offset:10016
	s_nop 3
	v_pk_mul_f32 v[66:67], v[50:51], v[66:67]
	v_pk_mul_f32 v[64:65], v[48:49], v[64:65]
	v_pk_fma_f32 v[122:123], v[122:123], v[46:47], v[66:67]
	v_pk_fma_f32 v[116:117], v[116:117], v[44:45], v[64:65]
	v_pk_mul_f32 v[238:239], v[50:51], v[238:239]
	v_pk_mul_f32 v[236:237], v[48:49], v[236:237]
	v_pk_fma_f32 v[126:127], v[126:127], v[46:47], v[238:239]
	v_pk_fma_f32 v[120:121], v[120:121], v[44:45], v[236:237]
	s_waitcnt lgkmcnt(6)
	v_mfma_f32_16x16x32_bf16 v[64:67], v[60:63], v[244:247], 0
	s_waitcnt lgkmcnt(4)
	v_mfma_f32_16x16x32_bf16 v[60:63], v[60:63], v[230:233], 0
	s_waitcnt lgkmcnt(2)
	v_mfma_f32_16x16x32_bf16 v[64:67], v[52:55], v[150:153], v[64:67]
	s_waitcnt lgkmcnt(0)
	s_barrier
	s_waitcnt lgkmcnt(0)
	v_mfma_f32_16x16x32_bf16 v[52:55], v[52:55], v[240:243], v[60:63]
	s_nop 4
	v_pk_mul_f32 v[66:67], v[50:51], v[66:67]
	v_pk_mul_f32 v[64:65], v[48:49], v[64:65]
	v_pk_fma_f32 v[128:129], v[128:129], v[46:47], v[66:67]
	v_pk_fma_f32 v[124:125], v[124:125], v[44:45], v[64:65]
	s_nop 7
	v_pk_mul_f32 v[48:49], v[48:49], v[52:53]
	v_pk_mul_f32 v[50:51], v[50:51], v[54:55]
	v_pk_fma_f32 v[130:131], v[130:131], v[44:45], v[48:49]
	v_mul_f32_e32 v44, v33, v33
	v_mul_f32_e32 v45, v35, v35
	v_fmac_f32_e32 v44, v32, v32
	v_fmac_f32_e32 v45, v34, v34
	v_pk_fma_f32 v[132:133], v[132:133], v[46:47], v[50:51]
	v_add_f32_e32 v44, v44, v45
	v_mul_f32_e32 v45, v41, v41
	v_mul_f32_e32 v46, v43, v43
	v_fmac_f32_e32 v45, v40, v40
	v_fmac_f32_e32 v46, v42, v42
	v_add_f32_e32 v45, v45, v46
	v_add_f32_e32 v44, v44, v45
	v_mul_f32_e32 v45, v57, v57
	v_mul_f32_e32 v46, v59, v59
	v_fmac_f32_e32 v45, v56, v56
	v_fmac_f32_e32 v46, v58, v58
	v_add_f32_e32 v45, v45, v46
	v_add_f32_e32 v44, v44, v45
	v_mul_f32_e32 v45, v37, v37
	v_mul_f32_e32 v46, v39, v39
	v_fmac_f32_e32 v45, v36, v36
	v_fmac_f32_e32 v46, v38, v38
	v_add_f32_e32 v45, v45, v46
	ds_read_b128 v[46:49], v197
	v_add_f32_e32 v44, v44, v45
	ds_bpermute_b32 v45, v249, v44
	s_waitcnt lgkmcnt(1)
	v_pk_mul_f32 v[50:51], v[104:105], v[48:49]
	v_pk_mul_f32 v[52:53], v[102:103], v[46:47]
	s_waitcnt lgkmcnt(0)
	v_add_f32_e32 v44, v44, v45
	v_cvt_pk_bf16_f32 v52, v52, v53
	v_cvt_pk_bf16_f32 v53, v50, v51
	ds_write_b64 v223, v[52:53]
	v_pk_mul_f32 v[50:51], v[114:115], v[48:49]
	v_pk_mul_f32 v[52:53], v[108:109], v[46:47]
	ds_bpermute_b32 v45, v250, v44
	v_cvt_pk_bf16_f32 v52, v52, v53
	v_cvt_pk_bf16_f32 v53, v50, v51
	ds_write_b64 v223, v[52:53] offset:4352
	v_pk_mul_f32 v[50:51], v[112:113], v[48:49]
	v_pk_mul_f32 v[52:53], v[106:107], v[46:47]
	s_nop 0
	v_cvt_pk_bf16_f32 v52, v52, v53
	v_cvt_pk_bf16_f32 v53, v50, v51
	ds_write_b64 v223, v[52:53] offset:8704
	v_pk_mul_f32 v[50:51], v[118:119], v[48:49]
	v_pk_mul_f32 v[52:53], v[110:111], v[46:47]
	s_nop 0
	v_cvt_pk_bf16_f32 v52, v52, v53
	v_cvt_pk_bf16_f32 v53, v50, v51
	ds_write_b64 v223, v[52:53] offset:13056
	v_pk_mul_f32 v[50:51], v[122:123], v[48:49]
	v_pk_mul_f32 v[52:53], v[116:117], v[46:47]
	s_nop 0
	v_cvt_pk_bf16_f32 v52, v52, v53
	v_cvt_pk_bf16_f32 v53, v50, v51
	ds_write_b64 v223, v[52:53] offset:17408
	v_pk_mul_f32 v[50:51], v[126:127], v[48:49]
	v_pk_mul_f32 v[52:53], v[120:121], v[46:47]
	s_nop 0
	v_cvt_pk_bf16_f32 v52, v52, v53
	v_cvt_pk_bf16_f32 v53, v50, v51
	ds_write_b64 v223, v[52:53] offset:21760
	v_pk_mul_f32 v[50:51], v[128:129], v[48:49]
	v_pk_mul_f32 v[52:53], v[124:125], v[46:47]
	v_pk_mul_f32 v[48:49], v[132:133], v[48:49]
	v_pk_mul_f32 v[46:47], v[130:131], v[46:47]
	v_cvt_pk_bf16_f32 v52, v52, v53
	v_cvt_pk_bf16_f32 v53, v50, v51
	v_cvt_pk_bf16_f32 v46, v46, v47
	v_cvt_pk_bf16_f32 v47, v48, v49
	ds_write_b64 v223, v[52:53] offset:26112
	ds_write_b64 v223, v[46:47] offset:30464
	s_and_saveexec_b64 s[52:53], s[16:17]
	s_cbranch_execz .LBB0_500
	s_waitcnt lgkmcnt(7)
	v_add_f32_e32 v44, v44, v45
	ds_write_b32 v184, v44
	s_branch .LBB0_500

; __global__ void __launch_bounds__(512, 2) fwd_megakernel(Args a) {
	.amdhsa_kernel _Z14fwd_megakernel4Args
		.amdhsa_group_segment_fixed_size 0
		.amdhsa_private_segment_fixed_size 0
		.amdhsa_kernarg_size 360
		.amdhsa_user_sgpr_count 2
		.amdhsa_user_sgpr_dispatch_ptr 0
		.amdhsa_user_sgpr_queue_ptr 0
		.amdhsa_user_sgpr_kernarg_segment_ptr 1
		.amdhsa_user_sgpr_dispatch_id 0
		.amdhsa_user_sgpr_kernarg_preload_length 0
		.amdhsa_user_sgpr_kernarg_preload_offset 0
		.amdhsa_user_sgpr_private_segment_size 0
		.amdhsa_uses_dynamic_stack 0
		.amdhsa_enable_private_segment 0
		.amdhsa_system_sgpr_workgroup_id_x 1
		.amdhsa_system_sgpr_workgroup_id_y 0
		.amdhsa_system_sgpr_workgroup_id_z 0
		.amdhsa_system_sgpr_workgroup_info 0
		.amdhsa_system_vgpr_workitem_id 2
		.amdhsa_next_free_vgpr 252
		.amdhsa_next_free_sgpr 102
		.amdhsa_accum_offset 252
		.amdhsa_reserve_vcc 1
		.amdhsa_float_round_mode_32 0
		.amdhsa_float_round_mode_16_64 0
		.amdhsa_float_denorm_mode_32 3
		.amdhsa_float_denorm_mode_16_64 3
		.amdhsa_dx10_clamp 1
		.amdhsa_ieee_mode 1
		.amdhsa_fp16_overflow 0
		.amdhsa_tg_split 0
		.amdhsa_exception_fp_ieee_invalid_op 0
		.amdhsa_exception_fp_denorm_src 0
		.amdhsa_exception_fp_ieee_div_zero 0
		.amdhsa_exception_fp_ieee_overflow 0
		.amdhsa_exception_fp_ieee_underflow 0
		.amdhsa_exception_fp_ieee_inexact 0
		.amdhsa_exception_int_div_zero 0
	.end_amdhsa_kernel

; __global__ void __launch_bounds__(512, 2) fwd_megakernel(Args a) {
amdhsa.kernels:
  - .agpr_count:     0
    .args:
      - .offset:         0
        .size:           104
        .value_kind:     by_value
      - .offset:         104
        .size:           4
        .value_kind:     hidden_block_count_x
      - .offset:         108
        .size:           4
        .value_kind:     hidden_block_count_y
      - .offset:         112
        .size:           4
        .value_kind:     hidden_block_count_z
      - .offset:         116
        .size:           2
        .value_kind:     hidden_group_size_x
      - .offset:         118
        .size:           2
        .value_kind:     hidden_group_size_y
      - .offset:         120
        .size:           2
        .value_kind:     hidden_group_size_z
      - .offset:         122
        .size:           2
        .value_kind:     hidden_remainder_x
      - .offset:         124
        .size:           2
        .value_kind:     hidden_remainder_y
      - .offset:         126
        .size:           2
        .value_kind:     hidden_remainder_z
      - .offset:         144
        .size:           8
        .value_kind:     hidden_global_offset_x
      - .offset:         152
        .size:           8
        .value_kind:     hidden_global_offset_y
      - .offset:         160
        .size:           8
        .value_kind:     hidden_global_offset_z
      - .offset:         168
        .size:           2
        .value_kind:     hidden_grid_dims
      - .offset:         192
        .size:           8
        .value_kind:     hidden_multigrid_sync_arg
      - .offset:         224
        .size:           4
        .value_kind:     hidden_dynamic_lds_size
    .group_segment_fixed_size: 0
    .kernarg_segment_align: 8
    .kernarg_segment_size: 360
    .language:       OpenCL C
    .language_version:
      - 2
      - 0
    .max_flat_workgroup_size: 512
    .name:           _Z14fwd_megakernel4Args
    .private_segment_fixed_size: 0
    .sgpr_count:     108
    .sgpr_spill_count: 6
    .symbol:         _Z14fwd_megakernel4Args.kd
    .uniform_work_group_size: 1
    .uses_dynamic_stack: false
    .vgpr_count:     252
    .vgpr_spill_count: 0
    .wavefront_size: 64
